# adds: hyena prompt gate pieces prefetched before the MFMA loop, odd workgroups run hyena units and attention/pool/prep units in the opposite order
# speedup vs baseline: 1.0282x; 1.0038x over previous
.LBB0_331:
	s_or_b64 exec, exec, s[42:43]
	v_readlane_b32 s0, v242, 8
	v_readlane_b32 s1, v242, 9
	s_xor_b64 s[0:1], s[0:1], -1
	v_writelane_b32 v242, s0, 18
	s_mov_b64 s[16:17], s[66:67]
	s_mov_b32 s28, s85
	v_writelane_b32 v242, s1, 19
	s_waitcnt lgkmcnt(0)
	v_readlane_b32 s0, v242, 12
	v_readlane_b32 s1, v242, 13
	s_mov_b32 s1, s41
	v_writelane_b32 v242, s0, 12
	s_barrier
	s_mov_b32 s29, s64
	s_and_b32 s98, s28, 1
	s_cmp_eq_u32 s98, 0
	s_cbranch_scc1 .Ll2_noswap
	s_cmpk_lg_i32 s29, 0x100
	s_cbranch_scc1 .Ll2_noswap
	s_addk_i32 s28, 0x800
	s_sub_i32 s29, 0, s29
.Ll2_noswap:
	s_cmpk_gt_i32 s28, 0x8ff
	v_writelane_b32 v242, s1, 13
	s_cbranch_scc1 .LBB0_444
	v_readlane_b32 s8, v242, 12
	s_mul_i32 s40, s8, 0x300
	s_mul_i32 s0, s8, 0x900
	s_mov_b32 s1, s41
	s_lshl_b32 s4, s8, 14
	s_mov_b32 s5, s41
	s_lshl_b32 s6, s8, 6
	s_mov_b32 s7, s41
	s_lshl_b32 s34, s28, 6
	s_lshl_b32 s30, s8, 8
	s_lshl_b32 s31, s8, 3
	s_lshl_b32 s35, s29, 6
	s_add_i32 s36, s34, 0xffff4000
	s_lshl_b64 s[18:19], s[40:41], 2
	s_lshl_b64 s[22:23], s[0:1], 2
	s_lshl_b64 s[24:25], s[4:5], 2
	s_lshl_b64 s[26:27], s[6:7], 2
	v_readlane_b32 s9, v242, 13
	s_branch .LBB0_335

.LBB0_334:
	s_add_i32 s28, s28, s29
	s_add_i32 s34, s34, s35
	s_add_i32 s36, s36, s35
	s_cmpk_gt_u32 s28, 0x8ff
	s_cbranch_scc1 .LBB0_444

.LBB0_491:
	s_mov_b64 s[4:5], s[66:67]
	s_mov_b32 s30, s85
	s_mov_b32 s31, s64
	s_and_b32 s98, s30, 1
	s_cmp_eq_u32 s98, 0
	s_cbranch_scc1 .Lhy_noswap
	s_cmpk_lg_i32 s31, 0x100
	s_cbranch_scc1 .Lhy_noswap
	s_addk_i32 s30, 0x100
	s_sub_i32 s31, 0, s31
.Lhy_noswap:
	s_cmpk_gt_u32 s30, 0x1ff
	s_cbranch_scc1 .LBB0_543
	s_load_dwordx2 s[4:5], s[4:5], 0xd8
	s_mul_i32 s40, s0, 0xc00000
	s_waitcnt lgkmcnt(0)
	s_add_u32 s1, s4, 0x18600000
	s_addc_u32 s2, s5, 0
	s_add_u32 s8, s4, 0x1ce00000
	s_addc_u32 s9, s5, 0
	s_and_b64 s[6:7], s[42:43], exec
	s_cselect_b32 s34, s2, s9
	s_cselect_b32 s35, s1, s8
	s_lshl_b64 s[6:7], s[40:41], 1
	s_add_u32 s6, s1, s6
	s_addc_u32 s7, s2, s7
	s_add_u32 s22, s6, 0x1800000
	s_addc_u32 s23, s7, 0
	s_and_b64 s[6:7], s[42:43], exec
	s_cselect_b32 s25, s9, s2
	s_cselect_b32 s24, s8, s1
	s_add_u32 s36, s4, 0xcd00000
	s_addc_u32 s37, s5, 0
	s_lshl_b32 s0, s0, 8
	s_or_b32 s44, s0, s48
	s_add_u32 s45, s4, 0x8c00000
	s_addc_u32 s46, s5, 0
	s_branch .LBB0_495

.LBB0_494:
	s_add_i32 s30, s30, s31
	s_cmpk_gt_u32 s30, 0x1ff
	s_cbranch_scc1 .LBB0_543

.LBB0_504:
	s_or_b64 exec, exec, s[4:5]
	v_sub_u32_e32 v2, 0, v10
	v_bfe_u32 v136, v10, 5, 1
	v_and_b32_e32 v0, 31, v10
	s_ashr_i32 s4, s1, 4
	v_and_b32_e32 v2, 3, v2
	s_and_b32 s1, s4, -4
	v_lshlrev_b32_e32 v139, 4, v136
	v_add_lshl_u32 v0, v2, v0, 1
	s_sub_i32 s7, s1, 31
	v_mul_u32_u24_e32 v3, 0x4440, v2
	s_add_i32 s2, 0, 0x11400
	v_sub_u32_e32 v2, v139, v0
	v_add3_u32 v2, s2, v3, v2
	s_lshl_b32 s2, s7, 8
	v_subrev_u32_e32 v2, s2, v2
	v_add_u32_e32 v4, 0x2140, v2
	s_waitcnt lgkmcnt(0)
	s_barrier
	v_add_u32_e32 v5, 0x2160, v2
	ds_read2_b64 v[108:111], v4 offset1:1
	ds_read2_b64 v[96:99], v5 offset1:1
	v_add_u32_e32 v4, 0x2180, v2
	v_add_u32_e32 v5, 0x21a0, v2
	ds_read2_b64 v[104:107], v4 offset1:1
	ds_read2_b64 v[92:95], v5 offset1:1
	v_add_u32_e32 v4, 0x21c0, v2
	v_add_u32_e32 v5, 0x21e0, v2
	ds_read2_b64 v[100:103], v4 offset1:1
	ds_read2_b64 v[84:87], v5 offset1:1
	v_add_u32_e32 v4, 0x2200, v2
	v_add_u32_e32 v5, 0x2220, v2
	ds_read2_b64 v[116:119], v4 offset1:1
	ds_read2_b64 v[112:115], v5 offset1:1
	v_add_u32_e32 v4, 0x2240, v2
	v_add_u32_e32 v5, 0x2260, v2
	ds_read2_b64 v[88:91], v4 offset1:1
	ds_read2_b64 v[76:79], v5 offset1:1
	v_add_u32_e32 v4, 0x2280, v2
	v_add_u32_e32 v5, 0x22a0, v2
	ds_read2_b64 v[80:83], v4 offset1:1
	ds_read2_b64 v[68:71], v5 offset1:1
	v_add_u32_e32 v4, 0x22c0, v2
	v_add_u32_e32 v2, 0x22e0, v2
	ds_read2_b64 v[72:75], v4 offset1:1
	ds_read2_b64 v[64:67], v2 offset1:1
	s_or_b32 s2, s4, 3
	s_lshl_b32 s4, s4, 8
	v_and_b32_e32 v137, 3, v10
	v_bfe_u32 v138, v10, 2, 3
	v_sub_u32_e32 v0, v3, v0
	s_and_b32 s4, s4, 0xfffffc00
	v_mul_u32_u24_e32 v1, 0x2240, v138
	s_add_i32 s5, 0, 0x11200
	v_mul_u32_u24_e32 v2, 0x110, v137
	v_subrev_u32_e32 v0, s4, v0
	v_mov_b32_e32 v48, 0
	v_add_u32_e32 v140, s5, v139
	v_add3_u32 v141, v1, v2, 0
	v_add_u32_e32 v142, 29, v137
	v_add_u32_e32 v143, 0, v0
	v_mov_b32_e32 v49, v48
	v_mov_b32_e32 v50, v48
	v_mov_b32_e32 v51, v48
	v_mov_b32_e32 v52, v48
	v_mov_b32_e32 v53, v48
	v_mov_b32_e32 v54, v48
	v_mov_b32_e32 v55, v48
	v_mov_b32_e32 v56, v48
	v_mov_b32_e32 v57, v48
	v_mov_b32_e32 v58, v48
	v_mov_b32_e32 v59, v48
	v_mov_b32_e32 v60, v48
	v_mov_b32_e32 v61, v48
	v_mov_b32_e32 v62, v48
	v_mov_b32_e32 v63, v48
	v_mov_b32_e32 v32, v48
	v_mov_b32_e32 v33, v48
	v_mov_b32_e32 v34, v48
	v_mov_b32_e32 v35, v48
	v_mov_b32_e32 v36, v48
	v_mov_b32_e32 v37, v48
	v_mov_b32_e32 v38, v48
	v_mov_b32_e32 v39, v48
	v_mov_b32_e32 v40, v48
	v_mov_b32_e32 v41, v48
	v_mov_b32_e32 v42, v48
	v_mov_b32_e32 v43, v48
	v_mov_b32_e32 v44, v48
	v_mov_b32_e32 v45, v48
	v_mov_b32_e32 v46, v48
	v_mov_b32_e32 v47, v48
	v_mov_b32_e32 v16, v48
	v_mov_b32_e32 v17, v48
	v_mov_b32_e32 v18, v48
	v_mov_b32_e32 v19, v48
	v_mov_b32_e32 v20, v48
	v_mov_b32_e32 v21, v48
	v_mov_b32_e32 v22, v48
	v_mov_b32_e32 v23, v48
	v_mov_b32_e32 v24, v48
	v_mov_b32_e32 v25, v48
	v_mov_b32_e32 v26, v48
	v_mov_b32_e32 v27, v48
	v_mov_b32_e32 v28, v48
	v_mov_b32_e32 v29, v48
	v_mov_b32_e32 v30, v48
	v_mov_b32_e32 v31, v48
	v_mov_b32_e32 v0, v48
	v_mov_b32_e32 v1, v48
	v_mov_b32_e32 v2, v48
	v_mov_b32_e32 v3, v48
	v_mov_b32_e32 v4, v48
	v_mov_b32_e32 v5, v48
	v_mov_b32_e32 v6, v48
	v_mov_b32_e32 v7, v48
	v_mov_b32_e32 v8, v48
	v_mov_b32_e32 v9, v48
	v_mov_b32_e32 v10, v48
	v_mov_b32_e32 v11, v48
	v_mov_b32_e32 v12, v48
	v_mov_b32_e32 v13, v48
	v_mov_b32_e32 v14, v48
	v_mov_b32_e32 v15, v48
	v_or_b32_e32 v222, s1, v137
	v_lshlrev_b32_e32 v223, 12, v138
	v_lshl_add_u32 v222, v222, 7, v223
	v_ashrrev_i32_e32 v223, 31, v222
	v_lshl_add_u64 v[222:223], v[222:223], 0, s[40:41]
	v_lshl_or_b32 v222, v136, 2, v222
	v_lshlrev_b64 v[222:223], 1, v[222:223]
	v_lshl_add_u64 v[222:223], s[22:23], 0, v[222:223]
	global_load_dwordx2 v[186:187], v[222:223], off
	global_load_dwordx2 v[188:189], v[222:223], off offset:16
	global_load_dwordx2 v[190:191], v[222:223], off offset:32
	global_load_dwordx2 v[192:193], v[222:223], off offset:48
	global_load_dwordx2 v[194:195], v[222:223], off offset:64
	global_load_dwordx2 v[196:197], v[222:223], off offset:80
	global_load_dwordx2 v[198:199], v[222:223], off offset:96
	global_load_dwordx2 v[200:201], v[222:223], off offset:112
	global_load_dwordx2 v[202:203], v[222:223], off offset:128
	global_load_dwordx2 v[204:205], v[222:223], off offset:144
	global_load_dwordx2 v[206:207], v[222:223], off offset:160
	global_load_dwordx2 v[208:209], v[222:223], off offset:176
	global_load_dwordx2 v[210:211], v[222:223], off offset:192
	global_load_dwordx2 v[212:213], v[222:223], off offset:208
	global_load_dwordx2 v[214:215], v[222:223], off offset:224
	global_load_dwordx2 v[220:221], v[222:223], off offset:240
	s_cmpk_lt_u32 s1, 16
	s_cbranch_scc1 .Lpb_a
	s_barrier

.LBB0_506:
	v_add_u32_e32 v120, 2, v142
	v_add_u32_e32 v145, v141, v139
	v_add_u32_e32 v121, 0x20f0, v145
	v_cmp_gt_u32_e32 vcc, 32, v120
	s_nop 1
	v_cndmask_b32_e64 v144, 0, 32, vcc
	v_cndmask_b32_e32 v154, v140, v121, vcc
	v_add_u32_e32 v124, v154, v144
	v_lshl_add_u32 v128, v144, 1, v154
	v_mad_u32_u24 v132, v144, 3, v154
	v_lshl_add_u32 v146, v144, 2, v154
	v_mad_u32_u24 v150, v144, 5, v154
	v_mad_u32_u24 v155, v144, 6, v154
	ds_read_b128 v[120:123], v154
	ds_read_b128 v[124:127], v124
	ds_read_b128 v[128:131], v128
	ds_read_b128 v[132:135], v132
	ds_read_b128 v[146:149], v146
	ds_read_b128 v[150:153], v150
	v_mad_u32_u24 v144, v144, 7, v154
	ds_read_b128 v[154:157], v155
	ds_read_b128 v[174:177], v144
	s_barrier
	s_setprio 1
	s_waitcnt lgkmcnt(7)
	v_mfma_f32_32x32x16_bf16 v[48:63], v[116:119], v[120:123], v[48:63]
	v_mfma_f32_32x32x16_bf16 v[32:47], v[100:103], v[120:123], v[32:47]
	v_mfma_f32_32x32x16_bf16 v[16:31], v[104:107], v[120:123], v[16:31]
	v_mfma_f32_32x32x16_bf16 v[0:15], v[108:111], v[120:123], v[0:15]
	s_waitcnt lgkmcnt(6)
	v_mfma_f32_32x32x16_bf16 v[48:63], v[112:115], v[124:127], v[48:63]
	v_mfma_f32_32x32x16_bf16 v[32:47], v[84:87], v[124:127], v[32:47]
	v_mfma_f32_32x32x16_bf16 v[16:31], v[92:95], v[124:127], v[16:31]
	v_mfma_f32_32x32x16_bf16 v[0:15], v[96:99], v[124:127], v[0:15]
	s_waitcnt lgkmcnt(5)
	v_mfma_f32_32x32x16_bf16 v[48:63], v[88:91], v[128:131], v[48:63]
	v_mfma_f32_32x32x16_bf16 v[32:47], v[116:119], v[128:131], v[32:47]
	v_mfma_f32_32x32x16_bf16 v[16:31], v[100:103], v[128:131], v[16:31]
	v_mfma_f32_32x32x16_bf16 v[0:15], v[104:107], v[128:131], v[0:15]
	s_waitcnt lgkmcnt(4)
	v_mfma_f32_32x32x16_bf16 v[48:63], v[76:79], v[132:135], v[48:63]
	v_mfma_f32_32x32x16_bf16 v[32:47], v[112:115], v[132:135], v[32:47]
	v_mfma_f32_32x32x16_bf16 v[16:31], v[84:87], v[132:135], v[16:31]
	v_mfma_f32_32x32x16_bf16 v[0:15], v[92:95], v[132:135], v[0:15]
	s_waitcnt lgkmcnt(3)
	v_mfma_f32_32x32x16_bf16 v[48:63], v[80:83], v[146:149], v[48:63]
	v_mfma_f32_32x32x16_bf16 v[32:47], v[88:91], v[146:149], v[32:47]
	v_mfma_f32_32x32x16_bf16 v[16:31], v[116:119], v[146:149], v[16:31]
	v_mfma_f32_32x32x16_bf16 v[0:15], v[100:103], v[146:149], v[0:15]
	s_waitcnt lgkmcnt(2)
	v_mfma_f32_32x32x16_bf16 v[48:63], v[68:71], v[150:153], v[48:63]
	v_mfma_f32_32x32x16_bf16 v[32:47], v[76:79], v[150:153], v[32:47]
	v_mfma_f32_32x32x16_bf16 v[16:31], v[112:115], v[150:153], v[16:31]
	v_mfma_f32_32x32x16_bf16 v[0:15], v[84:87], v[150:153], v[0:15]
	s_waitcnt lgkmcnt(1)
	v_mfma_f32_32x32x16_bf16 v[48:63], v[72:75], v[154:157], v[48:63]
	v_mfma_f32_32x32x16_bf16 v[32:47], v[80:83], v[154:157], v[32:47]
	v_mfma_f32_32x32x16_bf16 v[16:31], v[88:91], v[154:157], v[16:31]
	v_mfma_f32_32x32x16_bf16 v[0:15], v[116:119], v[154:157], v[0:15]
	s_waitcnt lgkmcnt(0)
	v_mfma_f32_32x32x16_bf16 v[48:63], v[64:67], v[174:177], v[48:63]
	v_mfma_f32_32x32x16_bf16 v[32:47], v[68:71], v[174:177], v[32:47]
	v_mfma_f32_32x32x16_bf16 v[16:31], v[76:79], v[174:177], v[16:31]
	v_mfma_f32_32x32x16_bf16 v[0:15], v[112:115], v[174:177], v[0:15]
	s_setprio 0
	s_barrier
	s_mov_b64 s[4:5], -1
	s_cmp_ge_i32 s7, s2
	s_cbranch_scc1 .LBB0_505
	v_add_u32_e32 v144, v143, v139
	v_add_u32_e32 v64, 0x15400, v144
	v_add_u32_e32 v69, 0x153e0, v144
	ds_read2_b64 v[64:67], v64 offset1:1
	ds_read2_b64 v[112:115], v69 offset1:1
	v_add_u32_e32 v69, 0x153c0, v144
	v_add_u32_e32 v70, 0x153a0, v144
	v_add_u32_e32 v72, 0x15340, v144
	v_add_u32_e32 v68, 0x15420, v144
	ds_read2_b64 v[124:127], v69 offset1:1
	ds_read2_b64 v[116:119], v70 offset1:1
	v_add_u32_e32 v69, 0x15380, v144
	v_add_u32_e32 v70, 0x15360, v144
	ds_read2_b64 v[128:131], v69 offset1:1
	ds_read2_b64 v[120:123], v70 offset1:1
	ds_read2_b64 v[68:71], v68 offset1:1
	ds_read2_b64 v[132:135], v72 offset1:1
	v_add_u32_e32 v72, 1, v142
	v_add_u32_e32 v73, 0x1fe0, v145
	v_cmp_gt_u32_e32 vcc, 32, v72
	s_nop 1
	v_cndmask_b32_e64 v154, 0, 32, vcc
	v_cndmask_b32_e32 v155, v140, v73, vcc
	v_add_u32_e32 v76, v155, v154
	v_lshl_add_u32 v80, v154, 1, v155
	v_mad_u32_u24 v88, v154, 3, v155
	v_lshl_add_u32 v146, v154, 2, v155
	v_mad_u32_u24 v150, v154, 5, v155
	v_mad_u32_u24 v156, v154, 6, v155
	ds_read_b128 v[72:75], v155
	ds_read_b128 v[76:79], v76
	ds_read_b128 v[80:83], v80
	ds_read_b128 v[88:91], v88
	ds_read_b128 v[146:149], v146
	ds_read_b128 v[150:153], v150
	v_mad_u32_u24 v158, v154, 7, v155
	ds_read_b128 v[154:157], v156
	ds_read_b128 v[174:177], v158
	s_barrier
	s_setprio 1
	s_waitcnt lgkmcnt(7)
	v_mfma_f32_32x32x16_bf16 v[48:63], v[64:67], v[72:75], v[48:63]
	v_mfma_f32_32x32x16_bf16 v[32:47], v[124:127], v[72:75], v[32:47]
	v_mfma_f32_32x32x16_bf16 v[16:31], v[128:131], v[72:75], v[16:31]
	v_mfma_f32_32x32x16_bf16 v[0:15], v[132:135], v[72:75], v[0:15]
	s_waitcnt lgkmcnt(6)
	v_mfma_f32_32x32x16_bf16 v[48:63], v[68:71], v[76:79], v[48:63]
	v_mfma_f32_32x32x16_bf16 v[32:47], v[112:115], v[76:79], v[32:47]
	v_mfma_f32_32x32x16_bf16 v[16:31], v[116:119], v[76:79], v[16:31]
	v_mfma_f32_32x32x16_bf16 v[0:15], v[120:123], v[76:79], v[0:15]
	s_waitcnt lgkmcnt(5)
	v_mfma_f32_32x32x16_bf16 v[48:63], v[108:111], v[80:83], v[48:63]
	v_mfma_f32_32x32x16_bf16 v[32:47], v[64:67], v[80:83], v[32:47]
	v_mfma_f32_32x32x16_bf16 v[16:31], v[124:127], v[80:83], v[16:31]
	v_mfma_f32_32x32x16_bf16 v[0:15], v[128:131], v[80:83], v[0:15]
	s_waitcnt lgkmcnt(4)
	v_mfma_f32_32x32x16_bf16 v[48:63], v[96:99], v[88:91], v[48:63]
	v_mfma_f32_32x32x16_bf16 v[32:47], v[68:71], v[88:91], v[32:47]
	v_mfma_f32_32x32x16_bf16 v[16:31], v[112:115], v[88:91], v[16:31]
	v_mfma_f32_32x32x16_bf16 v[0:15], v[116:119], v[88:91], v[0:15]
	s_waitcnt lgkmcnt(3)
	v_mfma_f32_32x32x16_bf16 v[48:63], v[104:107], v[146:149], v[48:63]
	v_mfma_f32_32x32x16_bf16 v[32:47], v[108:111], v[146:149], v[32:47]
	v_mfma_f32_32x32x16_bf16 v[16:31], v[64:67], v[146:149], v[16:31]
	v_mfma_f32_32x32x16_bf16 v[0:15], v[124:127], v[146:149], v[0:15]
	s_waitcnt lgkmcnt(2)
	v_mfma_f32_32x32x16_bf16 v[48:63], v[92:95], v[150:153], v[48:63]
	v_mfma_f32_32x32x16_bf16 v[32:47], v[96:99], v[150:153], v[32:47]
	v_mfma_f32_32x32x16_bf16 v[16:31], v[68:71], v[150:153], v[16:31]
	v_mfma_f32_32x32x16_bf16 v[0:15], v[112:115], v[150:153], v[0:15]
	s_waitcnt lgkmcnt(1)
	v_mfma_f32_32x32x16_bf16 v[48:63], v[100:103], v[154:157], v[48:63]
	v_mfma_f32_32x32x16_bf16 v[32:47], v[104:107], v[154:157], v[32:47]
	v_mfma_f32_32x32x16_bf16 v[16:31], v[108:111], v[154:157], v[16:31]
	v_mfma_f32_32x32x16_bf16 v[0:15], v[64:67], v[154:157], v[0:15]
	s_waitcnt lgkmcnt(0)
	v_mfma_f32_32x32x16_bf16 v[48:63], v[84:87], v[174:177], v[48:63]
	v_mfma_f32_32x32x16_bf16 v[32:47], v[92:95], v[174:177], v[32:47]
	v_mfma_f32_32x32x16_bf16 v[16:31], v[96:99], v[174:177], v[16:31]
	v_mfma_f32_32x32x16_bf16 v[0:15], v[68:71], v[174:177], v[0:15]
	s_setprio 0
	s_barrier
	s_add_i32 s6, s7, 2
	s_cmp_le_i32 s6, s2
	s_cbranch_scc0 .LBB0_505
	v_add_u32_e32 v88, 0x15240, v144
	v_add_u32_e32 v89, 0x15320, v144
	v_add_u32_e32 v64, 0x15300, v144
	v_add_u32_e32 v65, 0x152e0, v144
	v_add_u32_e32 v68, 0x152c0, v144
	v_add_u32_e32 v69, 0x152a0, v144
	v_add_u32_e32 v76, 0x15280, v144
	v_add_u32_e32 v77, 0x15260, v144
	v_add_u32_e32 v96, 0x1ed0, v145
	v_cmp_gt_u32_e32 vcc, 32, v142
	ds_read2_b64 v[84:87], v64 offset1:1
	ds_read2_b64 v[64:67], v65 offset1:1
	ds_read2_b64 v[72:75], v68 offset1:1
	ds_read2_b64 v[68:71], v69 offset1:1
	ds_read2_b64 v[80:83], v76 offset1:1
	ds_read2_b64 v[76:79], v77 offset1:1
	ds_read2_b64 v[92:95], v89 offset1:1
	ds_read2_b64 v[88:91], v88 offset1:1
	v_cndmask_b32_e64 v145, 0, 32, vcc
	v_cndmask_b32_e32 v154, v140, v96, vcc
	v_add_u32_e32 v100, v154, v145
	v_lshl_add_u32 v104, v145, 1, v154
	v_mad_u32_u24 v108, v145, 3, v154
	v_lshl_add_u32 v146, v145, 2, v154
	v_mad_u32_u24 v150, v145, 5, v154
	v_mad_u32_u24 v155, v145, 6, v154
	ds_read_b128 v[96:99], v154
	ds_read_b128 v[100:103], v100
	ds_read_b128 v[104:107], v104
	ds_read_b128 v[108:111], v108
	ds_read_b128 v[146:149], v146
	ds_read_b128 v[150:153], v150
	v_mad_u32_u24 v145, v145, 7, v154
	ds_read_b128 v[154:157], v155
	ds_read_b128 v[174:177], v145
	s_barrier
	s_setprio 1
	s_waitcnt lgkmcnt(7)
	v_mfma_f32_32x32x16_bf16 v[48:63], v[84:87], v[96:99], v[48:63]
	v_mfma_f32_32x32x16_bf16 v[32:47], v[72:75], v[96:99], v[32:47]
	v_mfma_f32_32x32x16_bf16 v[16:31], v[80:83], v[96:99], v[16:31]
	v_mfma_f32_32x32x16_bf16 v[0:15], v[88:91], v[96:99], v[0:15]
	s_waitcnt lgkmcnt(6)
	v_mfma_f32_32x32x16_bf16 v[48:63], v[92:95], v[100:103], v[48:63]
	v_mfma_f32_32x32x16_bf16 v[32:47], v[64:67], v[100:103], v[32:47]
	v_mfma_f32_32x32x16_bf16 v[16:31], v[68:71], v[100:103], v[16:31]
	v_mfma_f32_32x32x16_bf16 v[0:15], v[76:79], v[100:103], v[0:15]
	s_waitcnt lgkmcnt(5)
	v_mfma_f32_32x32x16_bf16 v[48:63], v[132:135], v[104:107], v[48:63]
	v_mfma_f32_32x32x16_bf16 v[32:47], v[84:87], v[104:107], v[32:47]
	v_mfma_f32_32x32x16_bf16 v[16:31], v[72:75], v[104:107], v[16:31]
	v_mfma_f32_32x32x16_bf16 v[0:15], v[80:83], v[104:107], v[0:15]
	s_waitcnt lgkmcnt(4)
	v_mfma_f32_32x32x16_bf16 v[48:63], v[120:123], v[108:111], v[48:63]
	v_mfma_f32_32x32x16_bf16 v[32:47], v[92:95], v[108:111], v[32:47]
	v_mfma_f32_32x32x16_bf16 v[16:31], v[64:67], v[108:111], v[16:31]
	v_mfma_f32_32x32x16_bf16 v[0:15], v[68:71], v[108:111], v[0:15]
	s_waitcnt lgkmcnt(3)
	v_mfma_f32_32x32x16_bf16 v[48:63], v[128:131], v[146:149], v[48:63]
	v_mfma_f32_32x32x16_bf16 v[32:47], v[132:135], v[146:149], v[32:47]
	v_mfma_f32_32x32x16_bf16 v[16:31], v[84:87], v[146:149], v[16:31]
	v_mfma_f32_32x32x16_bf16 v[0:15], v[72:75], v[146:149], v[0:15]
	s_waitcnt lgkmcnt(2)
	v_mfma_f32_32x32x16_bf16 v[48:63], v[116:119], v[150:153], v[48:63]
	v_mfma_f32_32x32x16_bf16 v[32:47], v[120:123], v[150:153], v[32:47]
	v_mfma_f32_32x32x16_bf16 v[16:31], v[92:95], v[150:153], v[16:31]
	v_mfma_f32_32x32x16_bf16 v[0:15], v[64:67], v[150:153], v[0:15]
	s_waitcnt lgkmcnt(1)
	v_mfma_f32_32x32x16_bf16 v[48:63], v[124:127], v[154:157], v[48:63]
	v_mfma_f32_32x32x16_bf16 v[32:47], v[128:131], v[154:157], v[32:47]
	v_mfma_f32_32x32x16_bf16 v[16:31], v[132:135], v[154:157], v[16:31]
	v_mfma_f32_32x32x16_bf16 v[0:15], v[84:87], v[154:157], v[0:15]
	s_waitcnt lgkmcnt(0)
	v_mfma_f32_32x32x16_bf16 v[48:63], v[112:115], v[174:177], v[48:63]
	v_mfma_f32_32x32x16_bf16 v[32:47], v[116:119], v[174:177], v[32:47]
	v_mfma_f32_32x32x16_bf16 v[16:31], v[120:123], v[174:177], v[16:31]
	v_mfma_f32_32x32x16_bf16 v[0:15], v[92:95], v[174:177], v[0:15]
	s_setprio 0
	s_barrier
	v_add_u32_e32 v84, 0x15140, v144
	v_add_u32_e32 v85, 0x15160, v144
	ds_read2_b64 v[108:111], v84 offset1:1
	ds_read2_b64 v[96:99], v85 offset1:1
	v_add_u32_e32 v84, 0x15180, v144
	v_add_u32_e32 v85, 0x151a0, v144
	ds_read2_b64 v[104:107], v84 offset1:1
	ds_read2_b64 v[92:95], v85 offset1:1
	v_add_u32_e32 v84, 0x151c0, v144
	v_add_u32_e32 v85, 0x151e0, v144
	v_add_u32_e32 v112, 0x15200, v144
	v_add_u32_e32 v113, 0x15220, v144
	ds_read2_b64 v[100:103], v84 offset1:1
	ds_read2_b64 v[84:87], v85 offset1:1
	ds_read2_b64 v[116:119], v112 offset1:1
	ds_read2_b64 v[112:115], v113 offset1:1
	s_add_i32 s6, s7, 3
	s_cmp_gt_i32 s6, s2
	v_add_u32_e32 v141, 0xfffffcd0, v141
	v_add_u32_e32 v142, -3, v142
	v_add_u32_e32 v143, 0xfffffd00, v143
	s_cselect_b64 s[4:5], -1, 0
	s_and_b64 vcc, exec, s[4:5]
	s_mov_b32 s7, s6
	s_cbranch_vccz .LBB0_506

.Lpb_b:
	v_or_b32_e32 v64, s1, v137
	v_lshlrev_b32_e32 v65, 12, v138
	v_lshl_add_u32 v64, v64, 7, v65
	v_ashrrev_i32_e32 v65, 31, v64
	v_lshl_add_u64 v[64:65], v[64:65], 0, s[40:41]
	v_lshl_or_b32 v64, v136, 2, v64
	v_lshlrev_b64 v[66:67], 1, v[64:65]
	v_lshl_add_u64 v[64:65], s[22:23], 0, v[66:67]
	v_lshl_add_u64 v[64:65], s[24:25], 0, v[66:67]
	s_mov_b64 s[4:5], 0
	s_waitcnt vmcnt(0)
	v_lshlrev_b32_e32 v224, 16, v186
	v_and_b32_e32 v225, 0xffff0000, v186
	v_lshlrev_b32_e32 v226, 16, v187
	v_and_b32_e32 v227, 0xffff0000, v187
	v_pk_mul_f32 v[48:49], v[48:49], v[224:225]
	v_pk_mul_f32 v[50:51], v[50:51], v[226:227]
	v_cvt_pk_bf16_f32 v48, v48, v49
	v_cvt_pk_bf16_f32 v49, v50, v51
	global_store_dwordx2 v[64:65], v[48:49], off
	v_lshlrev_b32_e32 v228, 16, v188
	v_and_b32_e32 v229, 0xffff0000, v188
	v_lshlrev_b32_e32 v230, 16, v189
	v_and_b32_e32 v231, 0xffff0000, v189
	v_pk_mul_f32 v[52:53], v[52:53], v[228:229]
	v_pk_mul_f32 v[54:55], v[54:55], v[230:231]
	v_cvt_pk_bf16_f32 v52, v52, v53
	v_cvt_pk_bf16_f32 v53, v54, v55
	global_store_dwordx2 v[64:65], v[52:53], off offset:16
	v_lshlrev_b32_e32 v224, 16, v190
	v_and_b32_e32 v225, 0xffff0000, v190
	v_lshlrev_b32_e32 v226, 16, v191
	v_and_b32_e32 v227, 0xffff0000, v191
	v_pk_mul_f32 v[56:57], v[56:57], v[224:225]
	v_pk_mul_f32 v[58:59], v[58:59], v[226:227]
	v_cvt_pk_bf16_f32 v56, v56, v57
	v_cvt_pk_bf16_f32 v57, v58, v59
	global_store_dwordx2 v[64:65], v[56:57], off offset:32
	v_lshlrev_b32_e32 v228, 16, v192
	v_and_b32_e32 v229, 0xffff0000, v192
	v_lshlrev_b32_e32 v230, 16, v193
	v_and_b32_e32 v231, 0xffff0000, v193
	v_pk_mul_f32 v[60:61], v[60:61], v[228:229]
	v_pk_mul_f32 v[62:63], v[62:63], v[230:231]
	v_cvt_pk_bf16_f32 v60, v60, v61
	v_cvt_pk_bf16_f32 v61, v62, v63
	global_store_dwordx2 v[64:65], v[60:61], off offset:48
	v_lshlrev_b32_e32 v224, 16, v194
	v_and_b32_e32 v225, 0xffff0000, v194
	v_lshlrev_b32_e32 v226, 16, v195
	v_and_b32_e32 v227, 0xffff0000, v195
	v_pk_mul_f32 v[32:33], v[32:33], v[224:225]
	v_pk_mul_f32 v[34:35], v[34:35], v[226:227]
	v_cvt_pk_bf16_f32 v32, v32, v33
	v_cvt_pk_bf16_f32 v33, v34, v35
	global_store_dwordx2 v[64:65], v[32:33], off offset:64
	v_lshlrev_b32_e32 v228, 16, v196
	v_and_b32_e32 v229, 0xffff0000, v196
	v_lshlrev_b32_e32 v230, 16, v197
	v_and_b32_e32 v231, 0xffff0000, v197
	v_pk_mul_f32 v[36:37], v[36:37], v[228:229]
	v_pk_mul_f32 v[38:39], v[38:39], v[230:231]
	v_cvt_pk_bf16_f32 v36, v36, v37
	v_cvt_pk_bf16_f32 v37, v38, v39
	global_store_dwordx2 v[64:65], v[36:37], off offset:80
	v_lshlrev_b32_e32 v224, 16, v198
	v_and_b32_e32 v225, 0xffff0000, v198
	v_lshlrev_b32_e32 v226, 16, v199
	v_and_b32_e32 v227, 0xffff0000, v199
	v_pk_mul_f32 v[40:41], v[40:41], v[224:225]
	v_pk_mul_f32 v[42:43], v[42:43], v[226:227]
	v_cvt_pk_bf16_f32 v40, v40, v41
	v_cvt_pk_bf16_f32 v41, v42, v43
	global_store_dwordx2 v[64:65], v[40:41], off offset:96
	v_lshlrev_b32_e32 v228, 16, v200
	v_and_b32_e32 v229, 0xffff0000, v200
	v_lshlrev_b32_e32 v230, 16, v201
	v_and_b32_e32 v231, 0xffff0000, v201
	v_pk_mul_f32 v[44:45], v[44:45], v[228:229]
	v_pk_mul_f32 v[46:47], v[46:47], v[230:231]
	v_cvt_pk_bf16_f32 v44, v44, v45
	v_cvt_pk_bf16_f32 v45, v46, v47
	global_store_dwordx2 v[64:65], v[44:45], off offset:112
	v_lshlrev_b32_e32 v224, 16, v202
	v_and_b32_e32 v225, 0xffff0000, v202
	v_lshlrev_b32_e32 v226, 16, v203
	v_and_b32_e32 v227, 0xffff0000, v203
	v_pk_mul_f32 v[16:17], v[16:17], v[224:225]
	v_pk_mul_f32 v[18:19], v[18:19], v[226:227]
	v_cvt_pk_bf16_f32 v16, v16, v17
	v_cvt_pk_bf16_f32 v17, v18, v19
	global_store_dwordx2 v[64:65], v[16:17], off offset:128
	v_lshlrev_b32_e32 v228, 16, v204
	v_and_b32_e32 v229, 0xffff0000, v204
	v_lshlrev_b32_e32 v230, 16, v205
	v_and_b32_e32 v231, 0xffff0000, v205
	v_pk_mul_f32 v[20:21], v[20:21], v[228:229]
	v_pk_mul_f32 v[22:23], v[22:23], v[230:231]
	v_cvt_pk_bf16_f32 v20, v20, v21
	v_cvt_pk_bf16_f32 v21, v22, v23
	global_store_dwordx2 v[64:65], v[20:21], off offset:144
	v_lshlrev_b32_e32 v224, 16, v206
	v_and_b32_e32 v225, 0xffff0000, v206
	v_lshlrev_b32_e32 v226, 16, v207
	v_and_b32_e32 v227, 0xffff0000, v207
	v_pk_mul_f32 v[24:25], v[24:25], v[224:225]
	v_pk_mul_f32 v[26:27], v[26:27], v[226:227]
	v_cvt_pk_bf16_f32 v24, v24, v25
	v_cvt_pk_bf16_f32 v25, v26, v27
	global_store_dwordx2 v[64:65], v[24:25], off offset:160
	v_lshlrev_b32_e32 v228, 16, v208
	v_and_b32_e32 v229, 0xffff0000, v208
	v_lshlrev_b32_e32 v230, 16, v209
	v_and_b32_e32 v231, 0xffff0000, v209
	v_pk_mul_f32 v[28:29], v[28:29], v[228:229]
	v_pk_mul_f32 v[30:31], v[30:31], v[230:231]
	v_cvt_pk_bf16_f32 v28, v28, v29
	v_cvt_pk_bf16_f32 v29, v30, v31
	global_store_dwordx2 v[64:65], v[28:29], off offset:176
	v_lshlrev_b32_e32 v224, 16, v210
	v_and_b32_e32 v225, 0xffff0000, v210
	v_lshlrev_b32_e32 v226, 16, v211
	v_and_b32_e32 v227, 0xffff0000, v211
	v_pk_mul_f32 v[0:1], v[0:1], v[224:225]
	v_pk_mul_f32 v[2:3], v[2:3], v[226:227]
	v_cvt_pk_bf16_f32 v0, v0, v1
	v_cvt_pk_bf16_f32 v1, v2, v3
	global_store_dwordx2 v[64:65], v[0:1], off offset:192
	v_lshlrev_b32_e32 v228, 16, v212
	v_and_b32_e32 v229, 0xffff0000, v212
	v_lshlrev_b32_e32 v230, 16, v213
	v_and_b32_e32 v231, 0xffff0000, v213
	v_pk_mul_f32 v[4:5], v[4:5], v[228:229]
	v_pk_mul_f32 v[6:7], v[6:7], v[230:231]
	v_cvt_pk_bf16_f32 v4, v4, v5
	v_cvt_pk_bf16_f32 v5, v6, v7
	global_store_dwordx2 v[64:65], v[4:5], off offset:208
	v_lshlrev_b32_e32 v224, 16, v214
	v_and_b32_e32 v225, 0xffff0000, v214
	v_lshlrev_b32_e32 v226, 16, v215
	v_and_b32_e32 v227, 0xffff0000, v215
	v_pk_mul_f32 v[8:9], v[8:9], v[224:225]
	v_pk_mul_f32 v[10:11], v[10:11], v[226:227]
	v_cvt_pk_bf16_f32 v8, v8, v9
	v_cvt_pk_bf16_f32 v9, v10, v11
	global_store_dwordx2 v[64:65], v[8:9], off offset:224
	v_lshlrev_b32_e32 v228, 16, v220
	v_and_b32_e32 v229, 0xffff0000, v220
	v_lshlrev_b32_e32 v230, 16, v221
	v_and_b32_e32 v231, 0xffff0000, v221
	v_pk_mul_f32 v[12:13], v[12:13], v[228:229]
	v_pk_mul_f32 v[14:15], v[14:15], v[230:231]
	v_cvt_pk_bf16_f32 v12, v12, v13
	v_cvt_pk_bf16_f32 v13, v14, v15
	global_store_dwordx2 v[64:65], v[12:13], off offset:240
	s_waitcnt lgkmcnt(0)
	s_barrier
